# attn_b: sixth LDS fragment slot, fragment prefetch depth 5 (was 4)
# speedup vs baseline: 1.0246x; 1.0016x over previous
.Lb_loopB:
	global_load_dwordx4 v[208:211], v71, s[96:97]
	global_load_dwordx4 v[212:215], v73, s[98:99]
	ds_read_b128 v[216:219], v75 offset:0
	ds_read_b128 v[220:223], v75 offset:64
	ds_read_b128 v[224:227], v75 offset:2560
	ds_read_b128 v[228:231], v75 offset:2624
	ds_read_b128 v[232:235], v75 offset:5120
	v_exp_f32_e32 v236, v88
	v_exp_f32_e32 v237, v89
	v_exp_f32_e32 v238, v90
	v_exp_f32_e32 v239, v91
	v_exp_f32_e32 v240, v92
	v_exp_f32_e32 v241, v93
	v_exp_f32_e32 v242, v94
	v_exp_f32_e32 v243, v95
	v_exp_f32_e32 v244, v96
	v_exp_f32_e32 v245, v97
	v_exp_f32_e32 v246, v98
	v_exp_f32_e32 v247, v99
	v_exp_f32_e32 v248, v100
	v_exp_f32_e32 v249, v101
	v_exp_f32_e32 v250, v102
	v_exp_f32_e32 v251, v103
	s_nop 0
	v_add_f32_e32 v67, v236, v237
	v_add_f32_e32 v67, v67, v238
	v_add_f32_e32 v67, v67, v239
	v_add_f32_e32 v67, v67, v240
	v_add_f32_e32 v67, v67, v241
	v_add_f32_e32 v67, v67, v242
	v_add_f32_e32 v67, v67, v243
	v_add_f32_e32 v67, v67, v244
	v_add_f32_e32 v67, v67, v245
	v_add_f32_e32 v67, v67, v246
	v_add_f32_e32 v67, v67, v247
	v_add_f32_e32 v67, v67, v248
	v_add_f32_e32 v67, v67, v249
	v_add_f32_e32 v67, v67, v250
	v_add_f32_e32 v67, v67, v251
	v_cmp_lt_f32_e32 vcc, s66, v67
	s_cbranch_vccnz .Lb_rare_B0_0

.Lb_back_B0_1:
	v_add_f32_e32 v64, v64, v67
	v_cvt_pk_bf16_f32 v184, v236, v237
	v_cvt_pk_bf16_f32 v185, v238, v239
	v_cvt_pk_bf16_f32 v186, v240, v241
	v_cvt_pk_bf16_f32 v187, v242, v243
	v_cvt_pk_bf16_f32 v204, v244, v245
	v_cvt_pk_bf16_f32 v205, v246, v247
	v_cvt_pk_bf16_f32 v206, v248, v249
	v_cvt_pk_bf16_f32 v207, v250, v251
	ds_read_b128 v[134:137], v75 offset:5184
	s_waitcnt lgkmcnt(5)
	v_mfma_f32_16x16x32_bf16 v[88:91], v[216:219], v[16:19], v[48:51]
	v_mfma_f32_16x16x32_bf16 v[104:107], v[216:219], v[12:15], v[52:55]
	ds_read_b128 v[216:219], v75 offset:7680
	s_waitcnt lgkmcnt(5)
	v_mfma_f32_16x16x32_bf16 v[88:91], v[220:223], v[8:11], v[88:91]
	v_mfma_f32_16x16x32_bf16 v[104:107], v[220:223], v[4:7], v[104:107]
	ds_read_b128 v[220:223], v75 offset:7744
	s_waitcnt lgkmcnt(5)
	v_mfma_f32_16x16x32_bf16 v[92:95], v[224:227], v[16:19], v[48:51]
	v_mfma_f32_16x16x32_bf16 v[168:171], v[224:227], v[12:15], v[52:55]
	ds_read_b64_tr_b16 v[224:225], v72 offset:20480
	ds_read_b64_tr_b16 v[226:227], v72 offset:23040
	s_waitcnt lgkmcnt(6)
	v_mfma_f32_16x16x32_bf16 v[92:95], v[228:231], v[8:11], v[92:95]
	v_mfma_f32_16x16x32_bf16 v[168:171], v[228:231], v[4:7], v[168:171]
	ds_read_b64_tr_b16 v[228:229], v72 offset:20512
	ds_read_b64_tr_b16 v[230:231], v72 offset:23072
	s_waitcnt lgkmcnt(7)
	v_mfma_f32_16x16x32_bf16 v[96:99], v[232:235], v[16:19], v[48:51]
	v_mfma_f32_16x16x32_bf16 v[172:175], v[232:235], v[12:15], v[52:55]
	ds_read_b64_tr_b16 v[232:233], v72 offset:20544
	ds_read_b64_tr_b16 v[234:235], v72 offset:23104
	s_waitcnt lgkmcnt(8)
	v_mfma_f32_16x16x32_bf16 v[96:99], v[134:137], v[8:11], v[96:99]
	v_mfma_f32_16x16x32_bf16 v[172:175], v[134:137], v[4:7], v[172:175]
	ds_read_b64_tr_b16 v[134:135], v72 offset:20576
	ds_read_b64_tr_b16 v[136:137], v72 offset:23136
	s_waitcnt lgkmcnt(9)
	v_mfma_f32_16x16x32_bf16 v[100:103], v[216:219], v[16:19], v[48:51]
	v_mfma_f32_16x16x32_bf16 v[176:179], v[216:219], v[12:15], v[52:55]
	ds_read_b64_tr_b16 v[216:217], v72 offset:25600
	ds_read_b64_tr_b16 v[218:219], v72 offset:28160
	s_waitcnt lgkmcnt(10)
	v_mfma_f32_16x16x32_bf16 v[100:103], v[220:223], v[8:11], v[100:103]
	v_mfma_f32_16x16x32_bf16 v[176:179], v[220:223], v[4:7], v[176:179]
	ds_read_b64_tr_b16 v[220:221], v72 offset:25632
	ds_read_b64_tr_b16 v[222:223], v72 offset:28192
	s_waitcnt lgkmcnt(10)
	v_mfma_f32_16x16x32_bf16 v[34:37], v[224:227], v[180:183], v[34:37]
	v_mfma_f32_16x16x32_bf16 v[20:23], v[224:227], v[184:187], v[20:23]
	ds_read_b64_tr_b16 v[224:225], v72 offset:25664
	ds_read_b64_tr_b16 v[226:227], v72 offset:28224
	s_waitcnt lgkmcnt(10)
	v_mfma_f32_16x16x32_bf16 v[42:45], v[228:231], v[180:183], v[42:45]
	v_mfma_f32_16x16x32_bf16 v[24:27], v[228:231], v[184:187], v[24:27]
	ds_read_b64_tr_b16 v[228:229], v72 offset:25696
	ds_read_b64_tr_b16 v[230:231], v72 offset:28256
	s_waitcnt lgkmcnt(10)
	v_mfma_f32_16x16x32_bf16 v[56:59], v[232:235], v[180:183], v[56:59]
	v_mfma_f32_16x16x32_bf16 v[38:41], v[232:235], v[184:187], v[38:41]
	s_waitcnt lgkmcnt(8)
	v_mfma_f32_16x16x32_bf16 v[60:63], v[134:137], v[180:183], v[60:63]
	v_mfma_f32_16x16x32_bf16 v[28:31], v[134:137], v[184:187], v[28:31]
	s_waitcnt lgkmcnt(6)
	v_mfma_f32_16x16x32_bf16 v[34:37], v[216:219], v[188:191], v[34:37]
	v_mfma_f32_16x16x32_bf16 v[20:23], v[216:219], v[204:207], v[20:23]
	s_waitcnt lgkmcnt(4)
	v_mfma_f32_16x16x32_bf16 v[42:45], v[220:223], v[188:191], v[42:45]
	v_mfma_f32_16x16x32_bf16 v[24:27], v[220:223], v[204:207], v[24:27]
	s_waitcnt lgkmcnt(2)
	v_mfma_f32_16x16x32_bf16 v[56:59], v[224:227], v[188:191], v[56:59]
	v_mfma_f32_16x16x32_bf16 v[38:41], v[224:227], v[204:207], v[38:41]
	s_waitcnt lgkmcnt(0)
	v_mfma_f32_16x16x32_bf16 v[60:63], v[228:231], v[188:191], v[60:63]
	v_mfma_f32_16x16x32_bf16 v[28:31], v[228:231], v[204:207], v[28:31]
	s_mov_b32 s42, s43
	s_mov_b32 s43, s51
	s_add_i32 s51, s51, 10240
	s_cmp_lg_u32 s51, 30720
	s_cselect_b32 s51, s51, 0
	s_min_u32 s8, s20, 60
	s_add_i32 s8, s8, 3
	s_mul_i32 s30, s8, 0xf8000
	s_nop 1
	s_waitcnt vmcnt(2)
	ds_write_b128 v120, v[138:141] offset:10240
	ds_write_b128 v74, v[142:145] offset:20480
	s_mov_b32 s66, 0xff800000
	s_mov_b32 s67, 0xff800000
	s_cmp_ge_u32 s20, 1
	s_cselect_b32 s66, 0x5f800000, s66
	s_cselect_b32 s67, 0x42000000, s67
	s_add_i32 s20, s20, 1
	v_add_u32_e32 v72, s42, v119
	v_add_u32_e32 v74, s51, v120
	s_add_u32 s96, s80, s30
	s_addc_u32 s97, s81, 0
	s_add_u32 s98, s86, s30
	s_addc_u32 s99, s87, 0
	s_waitcnt lgkmcnt(0)
	s_barrier
	global_load_dwordx4 v[138:141], v71, s[96:97]
	global_load_dwordx4 v[142:145], v73, s[98:99]
	ds_read_b128 v[216:219], v75 offset:10240
	ds_read_b128 v[220:223], v75 offset:10304
	ds_read_b128 v[224:227], v75 offset:12800
	ds_read_b128 v[228:231], v75 offset:12864
	ds_read_b128 v[232:235], v75 offset:15360
	v_exp_f32_e32 v236, v88
	v_exp_f32_e32 v237, v89
	v_exp_f32_e32 v238, v90
	v_exp_f32_e32 v239, v91
	v_exp_f32_e32 v240, v92
	v_exp_f32_e32 v241, v93
	v_exp_f32_e32 v242, v94
	v_exp_f32_e32 v243, v95
	v_exp_f32_e32 v244, v96
	v_exp_f32_e32 v245, v97
	v_exp_f32_e32 v246, v98
	v_exp_f32_e32 v247, v99
	v_exp_f32_e32 v248, v100
	v_exp_f32_e32 v249, v101
	v_exp_f32_e32 v250, v102
	v_exp_f32_e32 v251, v103
	s_nop 0
	v_add_f32_e32 v67, v236, v237
	v_add_f32_e32 v67, v67, v238
	v_add_f32_e32 v67, v67, v239
	v_add_f32_e32 v67, v67, v240
	v_add_f32_e32 v67, v67, v241
	v_add_f32_e32 v67, v67, v242
	v_add_f32_e32 v67, v67, v243
	v_add_f32_e32 v67, v67, v244
	v_add_f32_e32 v67, v67, v245
	v_add_f32_e32 v67, v67, v246
	v_add_f32_e32 v67, v67, v247
	v_add_f32_e32 v67, v67, v248
	v_add_f32_e32 v67, v67, v249
	v_add_f32_e32 v67, v67, v250
	v_add_f32_e32 v67, v67, v251
	v_cmp_lt_f32_e32 vcc, s66, v67
	s_cbranch_vccnz .Lb_rare_B1_0

.Lb_back_B1_1:
	v_add_f32_e32 v64, v64, v67
	v_cvt_pk_bf16_f32 v184, v236, v237
	v_cvt_pk_bf16_f32 v185, v238, v239
	v_cvt_pk_bf16_f32 v186, v240, v241
	v_cvt_pk_bf16_f32 v187, v242, v243
	v_cvt_pk_bf16_f32 v204, v244, v245
	v_cvt_pk_bf16_f32 v205, v246, v247
	v_cvt_pk_bf16_f32 v206, v248, v249
	v_cvt_pk_bf16_f32 v207, v250, v251
	ds_read_b128 v[134:137], v75 offset:15424
	s_waitcnt lgkmcnt(5)
	v_mfma_f32_16x16x32_bf16 v[88:91], v[216:219], v[16:19], v[48:51]
	v_mfma_f32_16x16x32_bf16 v[104:107], v[216:219], v[12:15], v[52:55]
	ds_read_b128 v[216:219], v75 offset:17920
	s_waitcnt lgkmcnt(5)
	v_mfma_f32_16x16x32_bf16 v[88:91], v[220:223], v[8:11], v[88:91]
	v_mfma_f32_16x16x32_bf16 v[104:107], v[220:223], v[4:7], v[104:107]
	ds_read_b128 v[220:223], v75 offset:17984
	s_waitcnt lgkmcnt(5)
	v_mfma_f32_16x16x32_bf16 v[92:95], v[224:227], v[16:19], v[48:51]
	v_mfma_f32_16x16x32_bf16 v[168:171], v[224:227], v[12:15], v[52:55]
	ds_read_b64_tr_b16 v[224:225], v72 offset:20480
	ds_read_b64_tr_b16 v[226:227], v72 offset:23040
	s_waitcnt lgkmcnt(6)
	v_mfma_f32_16x16x32_bf16 v[92:95], v[228:231], v[8:11], v[92:95]
	v_mfma_f32_16x16x32_bf16 v[168:171], v[228:231], v[4:7], v[168:171]
	ds_read_b64_tr_b16 v[228:229], v72 offset:20512
	ds_read_b64_tr_b16 v[230:231], v72 offset:23072
	s_waitcnt lgkmcnt(7)
	v_mfma_f32_16x16x32_bf16 v[96:99], v[232:235], v[16:19], v[48:51]
	v_mfma_f32_16x16x32_bf16 v[172:175], v[232:235], v[12:15], v[52:55]
	ds_read_b64_tr_b16 v[232:233], v72 offset:20544
	ds_read_b64_tr_b16 v[234:235], v72 offset:23104
	s_waitcnt lgkmcnt(8)
	v_mfma_f32_16x16x32_bf16 v[96:99], v[134:137], v[8:11], v[96:99]
	v_mfma_f32_16x16x32_bf16 v[172:175], v[134:137], v[4:7], v[172:175]
	ds_read_b64_tr_b16 v[134:135], v72 offset:20576
	ds_read_b64_tr_b16 v[136:137], v72 offset:23136
	s_waitcnt lgkmcnt(9)
	v_mfma_f32_16x16x32_bf16 v[100:103], v[216:219], v[16:19], v[48:51]
	v_mfma_f32_16x16x32_bf16 v[176:179], v[216:219], v[12:15], v[52:55]
	ds_read_b64_tr_b16 v[216:217], v72 offset:25600
	ds_read_b64_tr_b16 v[218:219], v72 offset:28160
	s_waitcnt lgkmcnt(10)
	v_mfma_f32_16x16x32_bf16 v[100:103], v[220:223], v[8:11], v[100:103]
	v_mfma_f32_16x16x32_bf16 v[176:179], v[220:223], v[4:7], v[176:179]
	ds_read_b64_tr_b16 v[220:221], v72 offset:25632
	ds_read_b64_tr_b16 v[222:223], v72 offset:28192
	s_waitcnt lgkmcnt(10)
	v_mfma_f32_16x16x32_bf16 v[34:37], v[224:227], v[180:183], v[34:37]
	v_mfma_f32_16x16x32_bf16 v[20:23], v[224:227], v[184:187], v[20:23]
	ds_read_b64_tr_b16 v[224:225], v72 offset:25664
	ds_read_b64_tr_b16 v[226:227], v72 offset:28224
	s_waitcnt lgkmcnt(10)
	v_mfma_f32_16x16x32_bf16 v[42:45], v[228:231], v[180:183], v[42:45]
	v_mfma_f32_16x16x32_bf16 v[24:27], v[228:231], v[184:187], v[24:27]
	ds_read_b64_tr_b16 v[228:229], v72 offset:25696
	ds_read_b64_tr_b16 v[230:231], v72 offset:28256
	s_waitcnt lgkmcnt(10)
	v_mfma_f32_16x16x32_bf16 v[56:59], v[232:235], v[180:183], v[56:59]
	v_mfma_f32_16x16x32_bf16 v[38:41], v[232:235], v[184:187], v[38:41]
	s_waitcnt lgkmcnt(8)
	v_mfma_f32_16x16x32_bf16 v[60:63], v[134:137], v[180:183], v[60:63]
	v_mfma_f32_16x16x32_bf16 v[28:31], v[134:137], v[184:187], v[28:31]
	s_waitcnt lgkmcnt(6)
	v_mfma_f32_16x16x32_bf16 v[34:37], v[216:219], v[188:191], v[34:37]
	v_mfma_f32_16x16x32_bf16 v[20:23], v[216:219], v[204:207], v[20:23]
	s_waitcnt lgkmcnt(4)
	v_mfma_f32_16x16x32_bf16 v[42:45], v[220:223], v[188:191], v[42:45]
	v_mfma_f32_16x16x32_bf16 v[24:27], v[220:223], v[204:207], v[24:27]
	s_waitcnt lgkmcnt(2)
	v_mfma_f32_16x16x32_bf16 v[56:59], v[224:227], v[188:191], v[56:59]
	v_mfma_f32_16x16x32_bf16 v[38:41], v[224:227], v[204:207], v[38:41]
	s_waitcnt lgkmcnt(0)
	v_mfma_f32_16x16x32_bf16 v[60:63], v[228:231], v[188:191], v[60:63]
	v_mfma_f32_16x16x32_bf16 v[28:31], v[228:231], v[204:207], v[28:31]
	s_mov_b32 s42, s43
	s_mov_b32 s43, s51
	s_add_i32 s51, s51, 10240
	s_cmp_lg_u32 s51, 30720
	s_cselect_b32 s51, s51, 0
	s_min_u32 s8, s20, 60
	s_add_i32 s8, s8, 3
	s_mul_i32 s30, s8, 0xf8000
	s_nop 1
	s_waitcnt vmcnt(2)
	ds_write_b128 v120, v[208:211] offset:0
	ds_write_b128 v74, v[212:215] offset:20480
	s_mov_b32 s66, 0xff800000
	s_mov_b32 s67, 0xff800000
	s_cmp_ge_u32 s20, 1
	s_cselect_b32 s66, 0x5f800000, s66
	s_cselect_b32 s67, 0x42000000, s67
	s_add_i32 s20, s20, 1
	v_add_u32_e32 v72, s42, v119
	v_add_u32_e32 v74, s51, v120
	s_add_u32 s96, s80, s30
	s_addc_u32 s97, s81, 0
	s_add_u32 s98, s86, s30
	s_addc_u32 s99, s87, 0
	s_waitcnt lgkmcnt(0)
	s_barrier
	s_cmp_lt_u32 s20, 64
	s_cbranch_scc1 .Lb_loopB
	v_add_u32_e32 v72, s42, v119
	ds_read_b64_tr_b16 v[216:217], v72 offset:20480
	ds_read_b64_tr_b16 v[218:219], v72 offset:23040
	ds_read_b64_tr_b16 v[220:221], v72 offset:20512
	ds_read_b64_tr_b16 v[222:223], v72 offset:23072
	ds_read_b64_tr_b16 v[224:225], v72 offset:20544
	ds_read_b64_tr_b16 v[226:227], v72 offset:23104
	ds_read_b64_tr_b16 v[228:229], v72 offset:20576
	ds_read_b64_tr_b16 v[230:231], v72 offset:23136
	ds_read_b64_tr_b16 v[232:233], v72 offset:25600
	ds_read_b64_tr_b16 v[234:235], v72 offset:28160
	v_exp_f32_e32 v236, v88
	v_exp_f32_e32 v237, v89
	v_exp_f32_e32 v238, v90
	v_exp_f32_e32 v239, v91
	v_exp_f32_e32 v240, v92
	v_exp_f32_e32 v241, v93
	v_exp_f32_e32 v242, v94
	v_exp_f32_e32 v243, v95
	v_exp_f32_e32 v244, v96
	v_exp_f32_e32 v245, v97
	v_exp_f32_e32 v246, v98
	v_exp_f32_e32 v247, v99
	v_exp_f32_e32 v248, v100
	v_exp_f32_e32 v249, v101
	v_exp_f32_e32 v250, v102
	v_exp_f32_e32 v251, v103
	s_nop 0
	v_add_f32_e32 v67, v236, v237
	v_add_f32_e32 v67, v67, v238
	v_add_f32_e32 v67, v67, v239
	v_add_f32_e32 v67, v67, v240
	v_add_f32_e32 v67, v67, v241
	v_add_f32_e32 v67, v67, v242
	v_add_f32_e32 v67, v67, v243
	v_add_f32_e32 v67, v67, v244
	v_add_f32_e32 v67, v67, v245
	v_add_f32_e32 v67, v67, v246
	v_add_f32_e32 v67, v67, v247
	v_add_f32_e32 v67, v67, v248
	v_add_f32_e32 v67, v67, v249
	v_add_f32_e32 v67, v67, v250
	v_add_f32_e32 v67, v67, v251
	v_cmp_lt_f32_e32 vcc, s66, v67
	s_cbranch_vccnz .Lb_rare_Bt_0

.Lb_back_Bt_1:
	v_add_f32_e32 v64, v64, v67
	v_cvt_pk_bf16_f32 v184, v236, v237
	v_cvt_pk_bf16_f32 v185, v238, v239
	v_cvt_pk_bf16_f32 v186, v240, v241
	v_cvt_pk_bf16_f32 v187, v242, v243
	v_cvt_pk_bf16_f32 v204, v244, v245
	v_cvt_pk_bf16_f32 v205, v246, v247
	v_cvt_pk_bf16_f32 v206, v248, v249
	v_cvt_pk_bf16_f32 v207, v250, v251
	ds_read_b64_tr_b16 v[134:135], v72 offset:25632
	ds_read_b64_tr_b16 v[136:137], v72 offset:28192
	s_waitcnt lgkmcnt(10)
	v_mfma_f32_16x16x32_bf16 v[34:37], v[216:219], v[180:183], v[34:37]
	v_mfma_f32_16x16x32_bf16 v[20:23], v[216:219], v[184:187], v[20:23]
	ds_read_b64_tr_b16 v[216:217], v72 offset:25664
	ds_read_b64_tr_b16 v[218:219], v72 offset:28224
	s_waitcnt lgkmcnt(10)
	v_mfma_f32_16x16x32_bf16 v[42:45], v[220:223], v[180:183], v[42:45]
	v_mfma_f32_16x16x32_bf16 v[24:27], v[220:223], v[184:187], v[24:27]
	ds_read_b64_tr_b16 v[220:221], v72 offset:25696
	ds_read_b64_tr_b16 v[222:223], v72 offset:28256
	s_waitcnt lgkmcnt(10)
	v_mfma_f32_16x16x32_bf16 v[56:59], v[224:227], v[180:183], v[56:59]
	v_mfma_f32_16x16x32_bf16 v[38:41], v[224:227], v[184:187], v[38:41]
	s_waitcnt lgkmcnt(8)
	v_mfma_f32_16x16x32_bf16 v[60:63], v[228:231], v[180:183], v[60:63]
	v_mfma_f32_16x16x32_bf16 v[28:31], v[228:231], v[184:187], v[28:31]
	s_waitcnt lgkmcnt(6)
	v_mfma_f32_16x16x32_bf16 v[34:37], v[232:235], v[188:191], v[34:37]
	v_mfma_f32_16x16x32_bf16 v[20:23], v[232:235], v[204:207], v[20:23]
	s_waitcnt lgkmcnt(4)
	v_mfma_f32_16x16x32_bf16 v[42:45], v[134:137], v[188:191], v[42:45]
	v_mfma_f32_16x16x32_bf16 v[24:27], v[134:137], v[204:207], v[24:27]
	s_waitcnt lgkmcnt(2)
	v_mfma_f32_16x16x32_bf16 v[56:59], v[216:219], v[188:191], v[56:59]
	v_mfma_f32_16x16x32_bf16 v[38:41], v[216:219], v[204:207], v[38:41]
	s_waitcnt lgkmcnt(0)
	v_mfma_f32_16x16x32_bf16 v[60:63], v[220:223], v[188:191], v[60:63]
	v_mfma_f32_16x16x32_bf16 v[28:31], v[220:223], v[204:207], v[28:31]
	s_waitcnt vmcnt(0)
	v_mov_b32_e32 v138, 0xa00
	v_mov_b32_e32 v139, 0x0
	v_mov_b32_e32 v140, 0x9ff
	v_mov_b32_e32 v141, 0x0
	v_mov_b32_e32 v142, 0x200
	v_mov_b32_e32 v143, 0x0
	v_mov_b32_e32 v144, 0x1ff
	v_mov_b32_e32 v145, 0x0
	s_branch .LBB0_666

.Lb_loopA:
	global_load_dwordx4 v[208:211], v71, s[96:97]
	global_load_dwordx4 v[212:215], v73, s[98:99]
	ds_read_b64_tr_b16 v[216:217], v72 offset:20480
	ds_read_b64_tr_b16 v[218:219], v72 offset:23040
	ds_read_b64_tr_b16 v[220:221], v72 offset:20512
	ds_read_b64_tr_b16 v[222:223], v72 offset:23072
	ds_read_b64_tr_b16 v[224:225], v72 offset:20544
	ds_read_b64_tr_b16 v[226:227], v72 offset:23104
	ds_read_b64_tr_b16 v[228:229], v72 offset:20576
	ds_read_b64_tr_b16 v[230:231], v72 offset:23136
	ds_read_b64_tr_b16 v[232:233], v72 offset:25600
	ds_read_b64_tr_b16 v[234:235], v72 offset:28160
	ds_read_b64_tr_b16 v[134:135], v72 offset:25632
	ds_read_b64_tr_b16 v[136:137], v72 offset:28192
	s_waitcnt lgkmcnt(10)
	v_mfma_f32_16x16x32_bf16 v[34:37], v[216:219], v[180:183], v[34:37]
	v_mfma_f32_16x16x32_bf16 v[20:23], v[216:219], v[184:187], v[20:23]
	ds_read_b64_tr_b16 v[216:217], v72 offset:25664
	ds_read_b64_tr_b16 v[218:219], v72 offset:28224
	s_waitcnt lgkmcnt(10)
	v_mfma_f32_16x16x32_bf16 v[42:45], v[220:223], v[180:183], v[42:45]
	v_mfma_f32_16x16x32_bf16 v[24:27], v[220:223], v[184:187], v[24:27]
	ds_read_b64_tr_b16 v[220:221], v72 offset:25696
	ds_read_b64_tr_b16 v[222:223], v72 offset:28256
	s_waitcnt lgkmcnt(10)
	v_mfma_f32_16x16x32_bf16 v[56:59], v[224:227], v[180:183], v[56:59]
	v_mfma_f32_16x16x32_bf16 v[38:41], v[224:227], v[184:187], v[38:41]
	ds_read_b128 v[224:227], v75 offset:0
	s_waitcnt lgkmcnt(9)
	v_mfma_f32_16x16x32_bf16 v[60:63], v[228:231], v[180:183], v[60:63]
	v_mfma_f32_16x16x32_bf16 v[28:31], v[228:231], v[184:187], v[28:31]
	ds_read_b128 v[228:231], v75 offset:64
	s_waitcnt lgkmcnt(8)
	v_mfma_f32_16x16x32_bf16 v[34:37], v[232:235], v[188:191], v[34:37]
	v_mfma_f32_16x16x32_bf16 v[20:23], v[232:235], v[204:207], v[20:23]
	ds_read_b128 v[232:235], v75 offset:2560
	s_waitcnt lgkmcnt(7)
	v_mfma_f32_16x16x32_bf16 v[42:45], v[134:137], v[188:191], v[42:45]
	v_mfma_f32_16x16x32_bf16 v[24:27], v[134:137], v[204:207], v[24:27]
	ds_read_b128 v[134:137], v75 offset:2624
	s_waitcnt lgkmcnt(6)
	v_mfma_f32_16x16x32_bf16 v[56:59], v[216:219], v[188:191], v[56:59]
	v_mfma_f32_16x16x32_bf16 v[38:41], v[216:219], v[204:207], v[38:41]
	ds_read_b128 v[216:219], v75 offset:5120
	s_waitcnt lgkmcnt(5)
	v_mfma_f32_16x16x32_bf16 v[60:63], v[220:223], v[188:191], v[60:63]
	v_mfma_f32_16x16x32_bf16 v[28:31], v[220:223], v[204:207], v[28:31]
	ds_read_b128 v[220:223], v75 offset:5184
	s_waitcnt lgkmcnt(5)
	v_mfma_f32_16x16x32_bf16 v[88:91], v[224:227], v[16:19], v[48:51]
	v_mfma_f32_16x16x32_bf16 v[104:107], v[224:227], v[12:15], v[52:55]
	ds_read_b128 v[224:227], v75 offset:7680
	s_waitcnt lgkmcnt(5)
	v_mfma_f32_16x16x32_bf16 v[88:91], v[228:231], v[8:11], v[88:91]
	v_mfma_f32_16x16x32_bf16 v[104:107], v[228:231], v[4:7], v[104:107]
	ds_read_b128 v[228:231], v75 offset:7744
	s_waitcnt lgkmcnt(5)
	v_mfma_f32_16x16x32_bf16 v[92:95], v[232:235], v[16:19], v[48:51]
	v_mfma_f32_16x16x32_bf16 v[168:171], v[232:235], v[12:15], v[52:55]
	s_waitcnt lgkmcnt(4)
	v_mfma_f32_16x16x32_bf16 v[92:95], v[134:137], v[8:11], v[92:95]
	v_mfma_f32_16x16x32_bf16 v[168:171], v[134:137], v[4:7], v[168:171]
	s_waitcnt lgkmcnt(3)
	v_mfma_f32_16x16x32_bf16 v[96:99], v[216:219], v[16:19], v[48:51]
	v_mfma_f32_16x16x32_bf16 v[172:175], v[216:219], v[12:15], v[52:55]
	s_waitcnt lgkmcnt(2)
	v_mfma_f32_16x16x32_bf16 v[96:99], v[220:223], v[8:11], v[96:99]
	v_mfma_f32_16x16x32_bf16 v[172:175], v[220:223], v[4:7], v[172:175]
	s_waitcnt lgkmcnt(1)
	v_mfma_f32_16x16x32_bf16 v[100:103], v[224:227], v[16:19], v[48:51]
	v_mfma_f32_16x16x32_bf16 v[176:179], v[224:227], v[12:15], v[52:55]
	s_waitcnt lgkmcnt(0)
	v_mfma_f32_16x16x32_bf16 v[100:103], v[228:231], v[8:11], v[100:103]
	v_mfma_f32_16x16x32_bf16 v[176:179], v[228:231], v[4:7], v[176:179]
	s_mov_b32 s42, s43
	s_mov_b32 s43, s51
	s_add_i32 s51, s51, 10240
	s_cmp_lg_u32 s51, 30720
	s_cselect_b32 s51, s51, 0
	s_min_u32 s8, s20, 60
	s_add_i32 s8, s8, 3
	s_mul_i32 s30, s8, 0xf8000
	s_nop 1
	v_exp_f32_e32 v236, v88
	v_exp_f32_e32 v237, v89
	v_exp_f32_e32 v238, v90
	v_exp_f32_e32 v239, v91
	v_exp_f32_e32 v240, v92
	v_exp_f32_e32 v241, v93
	v_exp_f32_e32 v242, v94
	v_exp_f32_e32 v243, v95
	v_exp_f32_e32 v244, v96
	v_exp_f32_e32 v245, v97
	v_exp_f32_e32 v246, v98
	v_exp_f32_e32 v247, v99
	v_exp_f32_e32 v248, v100
	v_exp_f32_e32 v249, v101
	v_exp_f32_e32 v250, v102
	v_exp_f32_e32 v251, v103
	s_nop 0
	v_add_f32_e32 v67, v236, v237
	v_add_f32_e32 v67, v67, v238
	v_add_f32_e32 v67, v67, v239
	v_add_f32_e32 v67, v67, v240
	v_add_f32_e32 v67, v67, v241
	v_add_f32_e32 v67, v67, v242
	v_add_f32_e32 v67, v67, v243
	v_add_f32_e32 v67, v67, v244
	v_add_f32_e32 v67, v67, v245
	v_add_f32_e32 v67, v67, v246
	v_add_f32_e32 v67, v67, v247
	v_add_f32_e32 v67, v67, v248
	v_add_f32_e32 v67, v67, v249
	v_add_f32_e32 v67, v67, v250
	v_add_f32_e32 v67, v67, v251
	v_cmp_lt_f32_e32 vcc, s66, v67
	s_cbranch_vccnz .Lb_rare_A0_0

.Lb_back_A0_1:
	v_add_f32_e32 v64, v64, v67
	v_cvt_pk_bf16_f32 v184, v236, v237
	v_cvt_pk_bf16_f32 v185, v238, v239
	v_cvt_pk_bf16_f32 v186, v240, v241
	v_cvt_pk_bf16_f32 v187, v242, v243
	v_cvt_pk_bf16_f32 v204, v244, v245
	v_cvt_pk_bf16_f32 v205, v246, v247
	v_cvt_pk_bf16_f32 v206, v248, v249
	v_cvt_pk_bf16_f32 v207, v250, v251
	s_waitcnt vmcnt(2)
	ds_write_b128 v120, v[138:141] offset:10240
	ds_write_b128 v74, v[142:145] offset:20480
	s_mov_b32 s66, 0x5f800000
	s_mov_b32 s67, 0x42000000
	s_add_i32 s20, s20, 1
	v_add_u32_e32 v72, s42, v119
	v_add_u32_e32 v74, s51, v120
	s_add_u32 s96, s80, s30
	s_addc_u32 s97, s81, 0
	s_add_u32 s98, s86, s30
	s_addc_u32 s99, s87, 0
	s_waitcnt lgkmcnt(0)
	s_barrier
	global_load_dwordx4 v[138:141], v71, s[96:97]
	global_load_dwordx4 v[142:145], v73, s[98:99]
	ds_read_b64_tr_b16 v[216:217], v72 offset:20480
	ds_read_b64_tr_b16 v[218:219], v72 offset:23040
	ds_read_b64_tr_b16 v[220:221], v72 offset:20512
	ds_read_b64_tr_b16 v[222:223], v72 offset:23072
	ds_read_b64_tr_b16 v[224:225], v72 offset:20544
	ds_read_b64_tr_b16 v[226:227], v72 offset:23104
	ds_read_b64_tr_b16 v[228:229], v72 offset:20576
	ds_read_b64_tr_b16 v[230:231], v72 offset:23136
	ds_read_b64_tr_b16 v[232:233], v72 offset:25600
	ds_read_b64_tr_b16 v[234:235], v72 offset:28160
	ds_read_b64_tr_b16 v[134:135], v72 offset:25632
	ds_read_b64_tr_b16 v[136:137], v72 offset:28192
	s_waitcnt lgkmcnt(10)
	v_mfma_f32_16x16x32_bf16 v[34:37], v[216:219], v[180:183], v[34:37]
	v_mfma_f32_16x16x32_bf16 v[20:23], v[216:219], v[184:187], v[20:23]
	ds_read_b64_tr_b16 v[216:217], v72 offset:25664
	ds_read_b64_tr_b16 v[218:219], v72 offset:28224
	s_waitcnt lgkmcnt(10)
	v_mfma_f32_16x16x32_bf16 v[42:45], v[220:223], v[180:183], v[42:45]
	v_mfma_f32_16x16x32_bf16 v[24:27], v[220:223], v[184:187], v[24:27]
	ds_read_b64_tr_b16 v[220:221], v72 offset:25696
	ds_read_b64_tr_b16 v[222:223], v72 offset:28256
	s_waitcnt lgkmcnt(10)
	v_mfma_f32_16x16x32_bf16 v[56:59], v[224:227], v[180:183], v[56:59]
	v_mfma_f32_16x16x32_bf16 v[38:41], v[224:227], v[184:187], v[38:41]
	ds_read_b128 v[224:227], v75 offset:10240
	s_waitcnt lgkmcnt(9)
	v_mfma_f32_16x16x32_bf16 v[60:63], v[228:231], v[180:183], v[60:63]
	v_mfma_f32_16x16x32_bf16 v[28:31], v[228:231], v[184:187], v[28:31]
	ds_read_b128 v[228:231], v75 offset:10304
	s_waitcnt lgkmcnt(8)
	v_mfma_f32_16x16x32_bf16 v[34:37], v[232:235], v[188:191], v[34:37]
	v_mfma_f32_16x16x32_bf16 v[20:23], v[232:235], v[204:207], v[20:23]
	ds_read_b128 v[232:235], v75 offset:12800
	s_waitcnt lgkmcnt(7)
	v_mfma_f32_16x16x32_bf16 v[42:45], v[134:137], v[188:191], v[42:45]
	v_mfma_f32_16x16x32_bf16 v[24:27], v[134:137], v[204:207], v[24:27]
	ds_read_b128 v[134:137], v75 offset:12864
	s_waitcnt lgkmcnt(6)
	v_mfma_f32_16x16x32_bf16 v[56:59], v[216:219], v[188:191], v[56:59]
	v_mfma_f32_16x16x32_bf16 v[38:41], v[216:219], v[204:207], v[38:41]
	ds_read_b128 v[216:219], v75 offset:15360
	s_waitcnt lgkmcnt(5)
	v_mfma_f32_16x16x32_bf16 v[60:63], v[220:223], v[188:191], v[60:63]
	v_mfma_f32_16x16x32_bf16 v[28:31], v[220:223], v[204:207], v[28:31]
	ds_read_b128 v[220:223], v75 offset:15424
	s_waitcnt lgkmcnt(5)
	v_mfma_f32_16x16x32_bf16 v[88:91], v[224:227], v[16:19], v[48:51]
	v_mfma_f32_16x16x32_bf16 v[104:107], v[224:227], v[12:15], v[52:55]
	ds_read_b128 v[224:227], v75 offset:17920
	s_waitcnt lgkmcnt(5)
	v_mfma_f32_16x16x32_bf16 v[88:91], v[228:231], v[8:11], v[88:91]
	v_mfma_f32_16x16x32_bf16 v[104:107], v[228:231], v[4:7], v[104:107]
	ds_read_b128 v[228:231], v75 offset:17984
	s_waitcnt lgkmcnt(5)
	v_mfma_f32_16x16x32_bf16 v[92:95], v[232:235], v[16:19], v[48:51]
	v_mfma_f32_16x16x32_bf16 v[168:171], v[232:235], v[12:15], v[52:55]
	s_waitcnt lgkmcnt(4)
	v_mfma_f32_16x16x32_bf16 v[92:95], v[134:137], v[8:11], v[92:95]
	v_mfma_f32_16x16x32_bf16 v[168:171], v[134:137], v[4:7], v[168:171]
	s_waitcnt lgkmcnt(3)
	v_mfma_f32_16x16x32_bf16 v[96:99], v[216:219], v[16:19], v[48:51]
	v_mfma_f32_16x16x32_bf16 v[172:175], v[216:219], v[12:15], v[52:55]
	s_waitcnt lgkmcnt(2)
	v_mfma_f32_16x16x32_bf16 v[96:99], v[220:223], v[8:11], v[96:99]
	v_mfma_f32_16x16x32_bf16 v[172:175], v[220:223], v[4:7], v[172:175]
	s_waitcnt lgkmcnt(1)
	v_mfma_f32_16x16x32_bf16 v[100:103], v[224:227], v[16:19], v[48:51]
	v_mfma_f32_16x16x32_bf16 v[176:179], v[224:227], v[12:15], v[52:55]
	s_waitcnt lgkmcnt(0)
	v_mfma_f32_16x16x32_bf16 v[100:103], v[228:231], v[8:11], v[100:103]
	v_mfma_f32_16x16x32_bf16 v[176:179], v[228:231], v[4:7], v[176:179]
	s_mov_b32 s42, s43
	s_mov_b32 s43, s51
	s_add_i32 s51, s51, 10240
	s_cmp_lg_u32 s51, 30720
	s_cselect_b32 s51, s51, 0
	s_min_u32 s8, s20, 60
	s_add_i32 s8, s8, 3
	s_mul_i32 s30, s8, 0xf8000
	s_nop 1
	v_exp_f32_e32 v236, v88
	v_exp_f32_e32 v237, v89
	v_exp_f32_e32 v238, v90
	v_exp_f32_e32 v239, v91
	v_exp_f32_e32 v240, v92
	v_exp_f32_e32 v241, v93
	v_exp_f32_e32 v242, v94
	v_exp_f32_e32 v243, v95
	v_exp_f32_e32 v244, v96
	v_exp_f32_e32 v245, v97
	v_exp_f32_e32 v246, v98
	v_exp_f32_e32 v247, v99
	v_exp_f32_e32 v248, v100
	v_exp_f32_e32 v249, v101
	v_exp_f32_e32 v250, v102
	v_exp_f32_e32 v251, v103
	s_nop 0
	v_add_f32_e32 v67, v236, v237
	v_add_f32_e32 v67, v67, v238
	v_add_f32_e32 v67, v67, v239
	v_add_f32_e32 v67, v67, v240
	v_add_f32_e32 v67, v67, v241
	v_add_f32_e32 v67, v67, v242
	v_add_f32_e32 v67, v67, v243
	v_add_f32_e32 v67, v67, v244
	v_add_f32_e32 v67, v67, v245
	v_add_f32_e32 v67, v67, v246
	v_add_f32_e32 v67, v67, v247
	v_add_f32_e32 v67, v67, v248
	v_add_f32_e32 v67, v67, v249
	v_add_f32_e32 v67, v67, v250
	v_add_f32_e32 v67, v67, v251
	v_cmp_lt_f32_e32 vcc, s66, v67
	s_cbranch_vccnz .Lb_rare_A1_0

.Lb_back_A1_1:
	v_add_f32_e32 v64, v64, v67
	v_cvt_pk_bf16_f32 v184, v236, v237
	v_cvt_pk_bf16_f32 v185, v238, v239
	v_cvt_pk_bf16_f32 v186, v240, v241
	v_cvt_pk_bf16_f32 v187, v242, v243
	v_cvt_pk_bf16_f32 v204, v244, v245
	v_cvt_pk_bf16_f32 v205, v246, v247
	v_cvt_pk_bf16_f32 v206, v248, v249
	v_cvt_pk_bf16_f32 v207, v250, v251
	s_waitcnt vmcnt(2)
	ds_write_b128 v120, v[208:211] offset:0
	ds_write_b128 v74, v[212:215] offset:20480
	s_mov_b32 s66, 0x5f800000
	s_mov_b32 s67, 0x42000000
	s_add_i32 s20, s20, 1
	v_add_u32_e32 v72, s42, v119
	v_add_u32_e32 v74, s51, v120
	s_add_u32 s96, s80, s30
	s_addc_u32 s97, s81, 0
	s_add_u32 s98, s86, s30
	s_addc_u32 s99, s87, 0
	s_waitcnt lgkmcnt(0)
	s_barrier
	s_cmp_lt_u32 s20, 64
	s_cbranch_scc1 .Lb_loopA
	v_add_u32_e32 v72, s42, v119
	ds_read_b64_tr_b16 v[216:217], v72 offset:20480
	ds_read_b64_tr_b16 v[218:219], v72 offset:23040
	ds_read_b64_tr_b16 v[220:221], v72 offset:20512
	ds_read_b64_tr_b16 v[222:223], v72 offset:23072
	ds_read_b64_tr_b16 v[224:225], v72 offset:20544
	ds_read_b64_tr_b16 v[226:227], v72 offset:23104
	ds_read_b64_tr_b16 v[228:229], v72 offset:20576
	ds_read_b64_tr_b16 v[230:231], v72 offset:23136
	ds_read_b64_tr_b16 v[232:233], v72 offset:25600
	ds_read_b64_tr_b16 v[234:235], v72 offset:28160
	ds_read_b64_tr_b16 v[134:135], v72 offset:25632
	ds_read_b64_tr_b16 v[136:137], v72 offset:28192
	s_waitcnt lgkmcnt(10)
	v_mfma_f32_16x16x32_bf16 v[34:37], v[216:219], v[180:183], v[34:37]
	v_mfma_f32_16x16x32_bf16 v[20:23], v[216:219], v[184:187], v[20:23]
	ds_read_b64_tr_b16 v[216:217], v72 offset:25664
	ds_read_b64_tr_b16 v[218:219], v72 offset:28224
	s_waitcnt lgkmcnt(10)
	v_mfma_f32_16x16x32_bf16 v[42:45], v[220:223], v[180:183], v[42:45]
	v_mfma_f32_16x16x32_bf16 v[24:27], v[220:223], v[184:187], v[24:27]
	ds_read_b64_tr_b16 v[220:221], v72 offset:25696
	ds_read_b64_tr_b16 v[222:223], v72 offset:28256
	s_waitcnt lgkmcnt(10)
	v_mfma_f32_16x16x32_bf16 v[56:59], v[224:227], v[180:183], v[56:59]
	v_mfma_f32_16x16x32_bf16 v[38:41], v[224:227], v[184:187], v[38:41]
	s_waitcnt lgkmcnt(8)
	v_mfma_f32_16x16x32_bf16 v[60:63], v[228:231], v[180:183], v[60:63]
	v_mfma_f32_16x16x32_bf16 v[28:31], v[228:231], v[184:187], v[28:31]
	s_waitcnt lgkmcnt(6)
	v_mfma_f32_16x16x32_bf16 v[34:37], v[232:235], v[188:191], v[34:37]
	v_mfma_f32_16x16x32_bf16 v[20:23], v[232:235], v[204:207], v[20:23]
	s_waitcnt lgkmcnt(4)
	v_mfma_f32_16x16x32_bf16 v[42:45], v[134:137], v[188:191], v[42:45]
	v_mfma_f32_16x16x32_bf16 v[24:27], v[134:137], v[204:207], v[24:27]
	s_waitcnt lgkmcnt(2)
	v_mfma_f32_16x16x32_bf16 v[56:59], v[216:219], v[188:191], v[56:59]
	v_mfma_f32_16x16x32_bf16 v[38:41], v[216:219], v[204:207], v[38:41]
	s_waitcnt lgkmcnt(0)
	v_mfma_f32_16x16x32_bf16 v[60:63], v[220:223], v[188:191], v[60:63]
	v_mfma_f32_16x16x32_bf16 v[28:31], v[220:223], v[204:207], v[28:31]
	s_waitcnt vmcnt(0)
	v_mov_b32_e32 v138, 0xa00
	v_mov_b32_e32 v139, 0x0
	v_mov_b32_e32 v140, 0x9ff
	v_mov_b32_e32 v141, 0x0
	v_mov_b32_e32 v142, 0x200
	v_mov_b32_e32 v143, 0x0
	v_mov_b32_e32 v144, 0x1ff
	v_mov_b32_e32 v145, 0x0
